# scan: all 330 v_pk_mul_f32/v_pk_add_f32 in the HGRN scan split into scalar f32 op pairs (bit-identical math)
# speedup vs baseline: 1.0015x; 1.0015x over previous
.LBB0_386:
	s_nop 7
	v_lshl_add_u32 v46, s89, 9, v106
	ds_read_b128 v[34:37], v46
	ds_read_b128 v[38:41], v46 offset:32
	ds_read_b128 v[42:45], v46 offset:64
	ds_read_b128 v[46:49], v46 offset:96
	s_movk_i32 s72, 0x8000
	s_waitcnt lgkmcnt(3)
	v_mul_f32_e32 v18, v18, v34
	v_mul_f32_e32 v19, v19, v35
	v_mul_f32_e32 v2, v2, v34
	v_mul_f32_e32 v3, v3, v35
	v_lshlrev_b32_e32 v34, 1, v85
	s_waitcnt lgkmcnt(2)
	v_mul_f32_e32 v22, v22, v38
	v_mul_f32_e32 v23, v23, v39
	v_mul_f32_e32 v6, v6, v38
	v_mul_f32_e32 v7, v7, v39
	v_add3_u32 v38, s88, v107, v34
	s_waitcnt lgkmcnt(0)
	v_mul_f32_e32 v32, v32, v48
	v_mul_f32_e32 v33, v33, v49
	v_mul_f32_e32 v28, v28, v44
	v_mul_f32_e32 v29, v29, v45
	v_mul_f32_e32 v24, v24, v40
	v_mul_f32_e32 v25, v25, v41
	v_mul_f32_e32 v20, v20, v36
	v_mul_f32_e32 v21, v21, v37
	v_mul_f32_e32 v30, v30, v46
	v_mul_f32_e32 v31, v31, v47
	v_mul_f32_e32 v26, v26, v42
	v_mul_f32_e32 v27, v27, v43
	v_mul_f32_e32 v16, v16, v48
	v_mul_f32_e32 v17, v17, v49
	v_mul_f32_e32 v12, v12, v44
	v_mul_f32_e32 v13, v13, v45
	v_mul_f32_e32 v8, v8, v40
	v_mul_f32_e32 v9, v9, v41
	v_mul_f32_e32 v4, v4, v36
	v_mul_f32_e32 v5, v5, v37
	v_mul_f32_e32 v14, v14, v46
	v_mul_f32_e32 v15, v15, v47
	v_mul_f32_e32 v10, v10, v42
	v_mul_f32_e32 v11, v11, v43
	v_add3_u32 v50, s88, v88, v34
	ds_read_b128 v[34:37], v38 offset:26112
	ds_read_b128 v[38:41], v38 offset:26144
	ds_read_b128 v[42:45], v50 offset:36352
	ds_read_b128 v[46:49], v50 offset:36384
	s_waitcnt lgkmcnt(1)
	v_mfma_f32_32x32x16_bf16 v[18:33], v[34:37], v[42:45], v[18:33]
	ds_read_b128 v[42:45], v50 offset:38912
	s_add_i32 s87, s87, 1
	s_mov_b32 s73, -1
	v_lshl_add_u64 v[80:81], v[80:81], 0, s[72:73]
	s_cmpk_lg_i32 s87, 0x81
	s_waitcnt lgkmcnt(0)
	v_mfma_f32_32x32x16_bf16 v[2:17], v[34:37], v[42:45], v[2:17]
	ds_read_b128 v[34:37], v50 offset:38944
	v_add_u32_e32 v42, 0x2000, v108
	v_mfma_f32_32x32x16_bf16 v[18:33], v[38:41], v[46:49], v[18:33]
	s_waitcnt lgkmcnt(0)
	v_mfma_f32_32x32x16_bf16 v[2:17], v[38:41], v[34:37], v[2:17]
	s_nop 9
	v_cvt_pk_bf16_f32 v34, v18, v19
	v_cvt_pk_bf16_f32 v35, v20, v21
	v_cvt_pk_bf16_f32 v38, v22, v23
	v_cvt_pk_bf16_f32 v39, v24, v25
	ds_write2_b64 v108, v[34:35], v[38:39] offset1:2
	v_cvt_pk_bf16_f32 v34, v26, v27
	v_cvt_pk_bf16_f32 v35, v28, v29
	v_cvt_pk_bf16_f32 v36, v2, v3
	v_cvt_pk_bf16_f32 v37, v4, v5
	v_cvt_pk_bf16_f32 v40, v6, v7
	v_cvt_pk_bf16_f32 v41, v8, v9
	v_cvt_pk_bf16_f32 v38, v30, v31
	v_cvt_pk_bf16_f32 v39, v32, v33
	ds_write2_b64 v42, v[36:37], v[40:41] offset0:64 offset1:66
	v_cvt_pk_bf16_f32 v36, v10, v11
	v_cvt_pk_bf16_f32 v37, v12, v13
	v_cvt_pk_bf16_f32 v40, v14, v15
	v_cvt_pk_bf16_f32 v41, v16, v17
	ds_write2_b64 v108, v[34:35], v[38:39] offset0:4 offset1:6
	ds_write2_b64 v42, v[36:37], v[40:41] offset0:68 offset1:70
	s_waitcnt lgkmcnt(0)
	s_barrier
	s_cbranch_scc0 .LBB0_395

.Lmy_sc_s88_wb0:
	v_lshlrev_b32_e32 v34, 1, v87
	v_lshlrev_b32_e32 v35, 1, v85
	v_add3_u32 v126, s88, v34, v35
	ds_read_b128 v[160:163], v126 offset:17408
	ds_read_b128 v[164:167], v126 offset:8704
	ds_read_b128 v[168:171], v126 offset:17440
	ds_read_b128 v[172:175], v126 offset:8736
	ds_read_b128 v[176:179], v126 offset:17472
	ds_read_b128 v[180:183], v126 offset:8768
	ds_read_b128 v[184:187], v126 offset:17504
	ds_read_b128 v[188:191], v126 offset:8800
	ds_read_b128 v[192:195], v126 offset:17536
	ds_read_b128 v[196:199], v126 offset:8832
	ds_read_b128 v[200:203], v126 offset:17568
	ds_read_b128 v[204:207], v126 offset:8864
	ds_read_b128 v[208:211], v126 offset:17600
	ds_read_b128 v[212:215], v126 offset:8896
	s_waitcnt lgkmcnt(12)
	v_mfma_f32_32x32x16_bf16 v[50:65], v[160:163], v[164:167], 0
	ds_read_b128 v[216:219], v126 offset:17632
	ds_read_b128 v[220:223], v126 offset:8928
	s_waitcnt lgkmcnt(12)
	v_mfma_f32_32x32x16_bf16 v[34:49], v[168:171], v[172:175], 0
	s_waitcnt lgkmcnt(10)
	v_mfma_f32_32x32x16_bf16 v[50:65], v[176:179], v[180:183], v[50:65]
	s_waitcnt lgkmcnt(8)
	v_mfma_f32_32x32x16_bf16 v[34:49], v[184:187], v[188:191], v[34:49]
	s_waitcnt lgkmcnt(6)
	v_mfma_f32_32x32x16_bf16 v[50:65], v[192:195], v[196:199], v[50:65]
	s_waitcnt lgkmcnt(4)
	v_mfma_f32_32x32x16_bf16 v[34:49], v[200:203], v[204:207], v[34:49]
	s_waitcnt lgkmcnt(2)
	v_mfma_f32_32x32x16_bf16 v[50:65], v[208:211], v[212:215], v[50:65]
	s_waitcnt lgkmcnt(0)
	v_mfma_f32_32x32x16_bf16 v[34:49], v[216:219], v[220:223], v[34:49]
	s_nop 11
	v_add_f32_e32 v110, v50, v34
	v_cndmask_b32_e64 v124, v110, 0, s[4:5]
	v_add_f32_e32 v110, v51, v35
	v_cndmask_b32_e64 v125, v110, 0, s[6:7]
	v_add_f32_e32 v110, v64, v48
	v_add_f32_e32 v111, v65, v49
	v_add_f32_e32 v112, v62, v46
	v_add_f32_e32 v113, v63, v47
	v_add_f32_e32 v114, v60, v44
	v_add_f32_e32 v115, v61, v45
	v_add_f32_e32 v116, v58, v42
	v_add_f32_e32 v117, v59, v43
	v_add_f32_e32 v118, v56, v40
	v_add_f32_e32 v119, v57, v41
	v_add_f32_e32 v120, v54, v38
	v_add_f32_e32 v121, v55, v39
	v_add_f32_e32 v122, v52, v36
	v_add_f32_e32 v123, v53, v37
	v_cvt_pk_bf16_f32 v120, v120, v121
	v_cvt_pk_bf16_f32 v122, v122, v123
	v_cvt_pk_bf16_f32 v118, v118, v119
	v_cvt_pk_bf16_f32 v116, v116, v117
	v_cvt_pk_bf16_f32 v114, v114, v115
	v_cvt_pk_bf16_f32 v112, v112, v113
	v_cvt_pk_bf16_f32 v110, v110, v111
	v_cndmask_b32_e64 v123, v122, 0, s[10:11]
	v_lshrrev_b32_e32 v122, 16, v122
	v_cndmask_b32_e64 v121, v120, 0, s[14:15]
	v_lshrrev_b32_e32 v120, 16, v120
	v_cndmask_b32_e64 v119, v118, 0, s[18:19]
	v_lshrrev_b32_e32 v118, 16, v118
	v_cndmask_b32_e64 v117, v116, 0, s[22:23]
	v_lshrrev_b32_e32 v116, 16, v116
	v_cndmask_b32_e64 v115, v114, 0, s[26:27]
	v_lshrrev_b32_e32 v114, 16, v114
	v_cndmask_b32_e64 v113, v112, 0, s[30:31]
	v_lshrrev_b32_e32 v112, 16, v112
	v_cndmask_b32_e64 v111, v110, 0, s[36:37]
	v_lshrrev_b32_e32 v110, 16, v110
	v_cndmask_b32_e64 v122, v122, 0, s[8:9]
	v_cndmask_b32_e64 v120, v120, 0, s[12:13]
	v_cndmask_b32_e64 v118, v118, 0, s[16:17]
	v_cndmask_b32_e64 v116, v116, 0, s[20:21]
	v_cndmask_b32_e64 v114, v114, 0, s[24:25]
	v_cndmask_b32_e64 v112, v112, 0, s[28:29]
	v_cndmask_b32_e64 v110, v110, 0, s[34:35]
	v_cvt_pk_bf16_f32 v124, v124, v125
	v_perm_b32 v125, v122, v123, s3
	v_add_u32_e32 v122, v89, v92
	v_perm_b32 v120, v120, v121, s3
	v_perm_b32 v121, v118, v119, s3
	v_perm_b32 v116, v116, v117, s3
	v_perm_b32 v117, v114, v115, s3
	v_perm_b32 v112, v112, v113, s3
	v_perm_b32 v113, v110, v111, s3
	ds_write_b64 v122, v[124:125]
	ds_write_b64 v93, v[120:121]
	ds_write_b64 v94, v[116:117]
	ds_write_b64 v95, v[112:113]

.LBB0_401:
	v_lshlrev_b32_e32 v106, 16, v65
	v_and_b32_e32 v107, 0xffff0000, v65
	v_lshlrev_b32_e32 v108, 16, v63
	v_and_b32_e32 v109, 0xffff0000, v63
	v_lshlrev_b32_e32 v110, 16, v64
	v_and_b32_e32 v111, 0xffff0000, v64
	v_lshlrev_b32_e32 v64, 16, v61
	v_and_b32_e32 v65, 0xffff0000, v61
	v_lshlrev_b32_e32 v112, 16, v62
	v_and_b32_e32 v113, 0xffff0000, v62
	v_lshlrev_b32_e32 v62, 16, v59
	v_and_b32_e32 v63, 0xffff0000, v59
	v_lshlrev_b32_e32 v114, 16, v80
	v_and_b32_e32 v115, 0xffff0000, v80
	v_lshlrev_b32_e32 v80, 16, v57
	v_and_b32_e32 v81, 0xffff0000, v57
	v_lshlrev_b32_e32 v116, 16, v58
	v_and_b32_e32 v117, 0xffff0000, v58
	v_lshlrev_b32_e32 v58, 16, v55
	v_and_b32_e32 v59, 0xffff0000, v55
	v_lshlrev_b32_e32 v118, 16, v56
	v_and_b32_e32 v119, 0xffff0000, v56
	v_lshlrev_b32_e32 v56, 16, v53
	v_and_b32_e32 v57, 0xffff0000, v53
	v_lshlrev_b32_e32 v120, 16, v54
	v_and_b32_e32 v121, 0xffff0000, v54
	v_lshlrev_b32_e32 v54, 16, v52
	v_and_b32_e32 v55, 0xffff0000, v52
	v_lshlrev_b32_e32 v52, 16, v60
	v_and_b32_e32 v53, 0xffff0000, v60
	v_exp_f32_e32 v60, v106
	v_exp_f32_e32 v61, v107
	v_add_f32_e32 v106, 0, v106
	v_add_f32_e32 v107, 0, v107
	v_exp_f32_e32 v126, v110
	v_exp_f32_e32 v127, v111
	v_add_f32_e32 v110, v106, v110
	v_add_f32_e32 v111, v107, v111
	v_exp_f32_e32 v128, v112
	v_exp_f32_e32 v129, v113
	v_add_f32_e32 v112, v110, v112
	v_add_f32_e32 v113, v111, v113
	v_exp_f32_e32 v134, v114
	v_exp_f32_e32 v135, v115
	v_add_f32_e32 v114, v112, v114
	v_add_f32_e32 v115, v113, v115
	v_exp_f32_e32 v136, v116
	v_exp_f32_e32 v137, v117
	v_add_f32_e32 v116, v114, v116
	v_add_f32_e32 v117, v115, v117
	v_exp_f32_e32 v142, v118
	v_exp_f32_e32 v143, v119
	v_add_f32_e32 v118, v116, v118
	v_add_f32_e32 v119, v117, v119
	v_exp_f32_e32 v144, v120
	v_exp_f32_e32 v145, v121
	v_add_f32_e32 v120, v118, v120
	v_add_f32_e32 v121, v119, v121
	v_exp_f32_e32 v152, v52
	v_add_f32_e32 v150, v120, v52
	v_add_f32_e32 v151, v121, v53
	v_exp_f32_e32 v153, v53
	v_mul_f32_e32 v52, v126, v60
	v_mul_f32_e32 v53, v127, v61
	v_mul_f32_e32 v108, v60, v108
	v_mul_f32_e32 v109, v61, v109
	v_sub_f32_e32 v124, 1.0, v60
	v_sub_f32_e32 v125, 1.0, v61
	v_mul_f32_e32 v60, v52, v64
	v_mul_f32_e32 v61, v53, v65
	v_mul_f32_e32 v52, v128, v52
	v_mul_f32_e32 v53, v129, v53
	v_lshlrev_b32_e32 v122, 16, v51
	v_mul_f32_e32 v62, v52, v62
	v_mul_f32_e32 v63, v53, v63
	v_mul_f32_e32 v52, v134, v52
	v_mul_f32_e32 v53, v135, v53
	v_and_b32_e32 v123, 0xffff0000, v51
	v_mul_f32_e32 v64, v52, v80
	v_mul_f32_e32 v65, v53, v81
	v_mul_f32_e32 v52, v136, v52
	v_mul_f32_e32 v53, v137, v53
	v_add_u32_e32 v51, s88, v97
	v_mul_f32_e32 v80, v52, v58
	v_mul_f32_e32 v81, v53, v59
	v_mul_f32_e32 v52, v142, v52
	v_mul_f32_e32 v53, v143, v53
	ds_write_b64 v51, v[150:151]
	v_sub_f32_e32 v130, 1.0, v126
	v_sub_f32_e32 v131, 1.0, v127
	v_mul_f32_e32 v126, v52, v56
	v_mul_f32_e32 v127, v53, v57
	v_mul_f32_e32 v56, v144, v52
	v_mul_f32_e32 v57, v145, v53
	s_waitcnt lgkmcnt(0)
	s_barrier
	v_sub_f32_e32 v132, 1.0, v128
	v_sub_f32_e32 v133, 1.0, v129
	v_mul_f32_e32 v128, v56, v54
	v_mul_f32_e32 v129, v57, v55
	ds_read2st64_b64 v[52:55], v97 offset1:1
	v_mul_f32_e32 v56, v152, v56
	v_mul_f32_e32 v57, v153, v57
	v_sub_f32_e32 v140, 1.0, v136
	v_sub_f32_e32 v141, 1.0, v137
	v_mul_f32_e32 v122, v56, v122
	v_mul_f32_e32 v123, v57, v123
	ds_read2st64_b64 v[56:59], v97 offset0:2 offset1:3
	s_waitcnt lgkmcnt(1)
	v_add_f32_e32 v52, 0, v52
	v_add_f32_e32 v53, 0, v53
	v_add_f32_e32 v52, v52, v54
	v_add_f32_e32 v53, v53, v55
	v_add_f32_e32 v54, 0, v54
	v_add_f32_e32 v55, 0, v55
	v_cndmask_b32_e64 v55, 0, v55, s[68:69]
	v_cndmask_b32_e64 v54, 0, v54, s[68:69]
	s_waitcnt lgkmcnt(0)
	v_add_f32_e32 v54, v56, v54
	v_add_f32_e32 v55, v57, v55
	v_cndmask_b32_e64 v55, 0, v55, s[70:71]
	v_cndmask_b32_e64 v54, 0, v54, s[70:71]
	v_add_f32_e32 v52, v52, v56
	v_add_f32_e32 v53, v53, v57
	v_add_f32_e32 v56, 0, v56
	v_add_f32_e32 v57, 0, v57
	v_add_f32_e32 v54, v58, v54
	v_add_f32_e32 v55, v59, v55
	v_cndmask_b32_e64 v55, 0, v55, s[72:73]
	v_cndmask_b32_e64 v105, 0, v54, s[72:73]
	v_add_f32_e32 v54, v56, v58
	v_add_f32_e32 v56, v57, v59
	v_add_f32_e32 v53, v53, v59
	v_sub_f32_e32 v136, v105, v54
	v_sub_f32_e32 v137, v55, v56
	v_sub_f32_e32 v138, 1.0, v134
	v_sub_f32_e32 v139, 1.0, v135
	v_sub_f32_e32 v146, 1.0, v142
	v_sub_f32_e32 v147, 1.0, v143
	v_sub_f32_e32 v134, 1.0, v152
	v_sub_f32_e32 v135, 1.0, v153
	v_add_f32_e32 v52, v52, v58
	v_sub_f32_e32 v142, v54, v105
	v_sub_f32_e32 v143, v56, v55
	v_exp_f32_e32 v54, v105
	v_sub_f32_e32 v152, v53, v55
	v_exp_f32_e64 v58, -v120
	v_exp_f32_e64 v59, -v121
	v_exp_f32_e32 v120, v136
	v_exp_f32_e32 v121, v137
	v_exp_f32_e32 v55, v55
	v_exp_f32_e64 v56, -v150
	v_exp_f32_e64 v57, -v151
	v_exp_f32_e32 v136, v142
	v_exp_f32_e32 v137, v143
	v_sub_f32_e32 v148, 1.0, v144
	v_sub_f32_e32 v149, 1.0, v145
	v_mul_f32_e32 v144, v122, v54
	v_mul_f32_e32 v145, v123, v55
	v_mul_f32_e32 v122, v122, v120
	v_mul_f32_e32 v123, v123, v121
	v_sub_f32_e32 v105, v52, v105
	v_cvt_pk_bf16_f32 v143, v122, v123
	v_mul_f32_e32 v122, v134, v56
	v_mul_f32_e32 v123, v135, v57
	v_exp_f32_e32 v142, v105
	v_mul_f32_e32 v56, v122, v136
	v_mul_f32_e32 v57, v123, v137
	v_cvt_pk_bf16_f32 v105, v144, v145
	v_cvt_pk_bf16_f32 v134, v56, v57
	v_mul_f32_e32 v56, v128, v54
	v_mul_f32_e32 v57, v129, v55
	v_exp_f32_e64 v118, -v118
	v_cvt_pk_bf16_f32 v56, v56, v57
	ds_write2_b32 v18, v105, v56 offset1:68
	v_mul_f32_e32 v56, v128, v120
	v_mul_f32_e32 v57, v129, v121
	v_exp_f32_e64 v119, -v119
	v_cvt_pk_bf16_f32 v56, v56, v57
	v_add_u32_e32 v57, 0x2000, v18
	v_mul_f32_e32 v58, v148, v58
	v_mul_f32_e32 v59, v149, v59
	ds_write2_b32 v57, v143, v56 offset0:128 offset1:196
	v_mul_f32_e32 v56, v58, v136
	v_mul_f32_e32 v57, v59, v137
	v_add_u32_e32 v105, 0x4400, v18
	v_cvt_pk_bf16_f32 v56, v56, v57
	ds_write2_b32 v105, v134, v56 offset1:68
	v_mul_f32_e32 v56, v126, v54
	v_mul_f32_e32 v57, v127, v55
	v_mul_f32_e32 v118, v146, v118
	v_mul_f32_e32 v119, v147, v119
	v_cvt_pk_bf16_f32 v128, v56, v57
	v_mul_f32_e32 v56, v126, v120
	v_mul_f32_e32 v57, v127, v121
	v_exp_f32_e64 v116, -v116
	v_exp_f32_e64 v117, -v117
	v_cvt_pk_bf16_f32 v126, v56, v57
	v_mul_f32_e32 v56, v118, v136
	v_mul_f32_e32 v57, v119, v137
	v_exp_f32_e64 v114, -v114
	v_cvt_pk_bf16_f32 v127, v56, v57
	v_mul_f32_e32 v56, v80, v54
	v_mul_f32_e32 v57, v81, v55
	v_exp_f32_e64 v115, -v115
	v_cvt_pk_bf16_f32 v56, v56, v57
	ds_write2_b32 v18, v128, v56 offset0:136 offset1:204
	v_mul_f32_e32 v56, v80, v120
	v_mul_f32_e32 v57, v81, v121
	v_add_u32_e32 v128, 0x2400, v18
	v_cvt_pk_bf16_f32 v56, v56, v57
	v_mul_f32_e32 v80, v140, v116
	v_mul_f32_e32 v81, v141, v117
	ds_write2_b32 v128, v126, v56 offset0:8 offset1:76
	v_mul_f32_e32 v56, v80, v136
	v_mul_f32_e32 v57, v81, v137
	v_exp_f32_e64 v112, -v112
	v_cvt_pk_bf16_f32 v56, v56, v57
	ds_write2_b32 v105, v127, v56 offset0:136 offset1:204
	v_mul_f32_e32 v56, v64, v54
	v_mul_f32_e32 v57, v65, v55
	v_exp_f32_e64 v113, -v113
	v_cvt_pk_bf16_f32 v105, v56, v57
	v_mul_f32_e32 v56, v64, v120
	v_mul_f32_e32 v57, v65, v121
	v_mul_f32_e32 v64, v138, v114
	v_mul_f32_e32 v65, v139, v115
	v_cvt_pk_bf16_f32 v116, v56, v57
	v_mul_f32_e32 v56, v64, v136
	v_mul_f32_e32 v57, v65, v137
	v_add_u32_e32 v115, 0x400, v18
	v_cvt_pk_bf16_f32 v114, v56, v57
	v_mul_f32_e32 v56, v62, v54
	v_mul_f32_e32 v57, v63, v55
	v_exp_f32_e64 v110, -v110
	v_cvt_pk_bf16_f32 v56, v56, v57
	ds_write2_b32 v115, v105, v56 offset0:16 offset1:84
	v_mul_f32_e32 v56, v62, v120
	v_mul_f32_e32 v57, v63, v121
	v_mul_f32_e32 v62, v132, v112
	v_mul_f32_e32 v63, v133, v113
	v_cvt_pk_bf16_f32 v56, v56, v57
	ds_write2_b32 v128, v116, v56 offset0:144 offset1:212
	v_mul_f32_e32 v56, v62, v136
	v_mul_f32_e32 v57, v63, v137
	v_exp_f32_e64 v111, -v111
	v_exp_f32_e64 v106, -v106
	v_exp_f32_e64 v107, -v107
	v_cvt_pk_bf16_f32 v56, v56, v57
	v_add_u32_e32 v105, 0x4800, v18
	ds_write2_b32 v105, v114, v56 offset0:16 offset1:84
	v_mul_f32_e32 v56, v60, v54
	v_mul_f32_e32 v57, v61, v55
	v_mul_f32_e32 v54, v108, v54
	v_mul_f32_e32 v55, v109, v55
	v_cvt_pk_bf16_f32 v112, v56, v57
	v_cvt_pk_bf16_f32 v54, v54, v55
	v_mul_f32_e32 v56, v60, v120
	v_mul_f32_e32 v57, v61, v121
	ds_write2_b32 v115, v112, v54 offset0:152 offset1:220
	v_mul_f32_e32 v54, v108, v120
	v_mul_f32_e32 v55, v109, v121
	v_cvt_pk_bf16_f32 v113, v56, v57
	v_mul_f32_e32 v60, v130, v110
	v_mul_f32_e32 v61, v131, v111
	v_cvt_pk_bf16_f32 v54, v54, v55
	v_add_u32_e32 v55, 0x2800, v18
	v_mul_f32_e32 v106, v124, v106
	v_mul_f32_e32 v107, v125, v107
	v_mul_f32_e32 v56, v60, v136
	v_mul_f32_e32 v57, v61, v137
	ds_write2_b32 v55, v113, v54 offset0:24 offset1:92
	v_mul_f32_e32 v54, v106, v136
	v_mul_f32_e32 v55, v107, v137
	v_cvt_pk_bf16_f32 v56, v56, v57
	v_cvt_pk_bf16_f32 v54, v54, v55
	ds_write2_b32 v105, v56, v54 offset0:152 offset1:220
	v_exp_f32_e32 v108, v152
	v_mov_b32_e32 v54, v122
	v_mov_b32_e32 v55, v58
	v_mov_b32_e32 v56, v118
	v_mov_b32_e32 v57, v80
	v_mul_f32_e32 v54, v54, v142
	v_mul_f32_e32 v55, v55, v142
	v_mul_f32_e32 v56, v56, v142
	v_mul_f32_e32 v57, v57, v142
	v_cvt_pk_bf16_f32 v54, v54, v55
	v_cvt_pk_bf16_f32 v55, v56, v57
	v_mov_b32_e32 v56, v64
	v_mov_b32_e32 v57, v62
	v_mov_b32_e32 v110, v60
	v_mov_b32_e32 v111, v106
	v_mul_f32_e32 v56, v56, v142
	v_mul_f32_e32 v57, v57, v142
	v_mul_f32_e32 v110, v110, v142
	v_mul_f32_e32 v111, v111, v142
	v_mov_b32_e32 v62, v65
	v_cvt_pk_bf16_f32 v56, v56, v57
	v_cvt_pk_bf16_f32 v57, v110, v111
	v_mov_b32_e32 v58, v123
	v_mov_b32_e32 v80, v119
	v_mul_f32_e32 v62, v62, v108
	v_mul_f32_e32 v63, v63, v108
	v_mov_b32_e32 v106, v61
	v_mul_f32_e32 v58, v58, v108
	v_mul_f32_e32 v59, v59, v108
	v_mul_f32_e32 v80, v80, v108
	v_mul_f32_e32 v81, v81, v108
	v_cvt_pk_bf16_f32 v60, v62, v63
	v_mul_f32_e32 v62, v106, v108
	v_mul_f32_e32 v63, v107, v108
	ds_write_b128 v16, v[54:57] offset:26112
	v_cndmask_b32_e64 v54, 0, 1, s[68:69]
	v_cvt_pk_bf16_f32 v58, v58, v59
	v_cvt_pk_bf16_f32 v59, v80, v81
	v_cvt_pk_bf16_f32 v61, v62, v63
	v_cmp_ne_u32_e64 s[74:75], 1, v54
	s_andn2_b64 vcc, exec, s[68:69]
	ds_write_b128 v16, v[58:61] offset:26192
	s_cbranch_vccnz .LBB0_403
	v_exp_f32_e32 v52, v52
	v_exp_f32_e32 v53, v53
	ds_write_b64 v98, v[52:53]

.LBB0_405:
	v_lshlrev_b32_e32 v106, 16, v50
	v_and_b32_e32 v107, 0xffff0000, v50
	v_lshlrev_b32_e32 v110, 16, v48
	v_and_b32_e32 v111, 0xffff0000, v48
	v_exp_f32_e32 v122, v106
	v_exp_f32_e32 v123, v107
	v_add_f32_e32 v106, 0, v106
	v_add_f32_e32 v107, 0, v107
	v_lshlrev_b32_e32 v112, 16, v46
	v_and_b32_e32 v113, 0xffff0000, v46
	v_exp_f32_e32 v128, v110
	v_exp_f32_e32 v129, v111
	v_add_f32_e32 v110, v106, v110
	v_add_f32_e32 v111, v107, v111
	v_lshlrev_b32_e32 v108, 16, v49
	v_and_b32_e32 v109, 0xffff0000, v49
	v_lshlrev_b32_e32 v48, 16, v47
	v_and_b32_e32 v49, 0xffff0000, v47
	v_lshlrev_b32_e32 v46, 16, v44
	v_and_b32_e32 v47, 0xffff0000, v44
	v_lshlrev_b32_e32 v44, 16, v45
	v_and_b32_e32 v45, 0xffff0000, v45
	v_exp_f32_e32 v130, v112
	v_exp_f32_e32 v131, v113
	v_add_f32_e32 v112, v110, v112
	v_add_f32_e32 v113, v111, v113
	v_lshlrev_b32_e32 v116, 16, v42
	v_and_b32_e32 v117, 0xffff0000, v42
	v_exp_f32_e32 v136, v44
	v_exp_f32_e32 v137, v45
	v_add_f32_e32 v44, v112, v44
	v_add_f32_e32 v45, v113, v45
	v_lshlrev_b32_e32 v114, 16, v43
	v_and_b32_e32 v115, 0xffff0000, v43
	v_lshlrev_b32_e32 v42, 16, v40
	v_and_b32_e32 v43, 0xffff0000, v40
	v_lshlrev_b32_e32 v40, 16, v41
	v_and_b32_e32 v41, 0xffff0000, v41
	v_exp_f32_e32 v138, v116
	v_exp_f32_e32 v139, v117
	v_add_f32_e32 v116, v44, v116
	v_add_f32_e32 v117, v45, v117
	v_lshlrev_b32_e32 v118, 16, v38
	v_and_b32_e32 v119, 0xffff0000, v38
	v_lshlrev_b32_e32 v38, 16, v39
	v_and_b32_e32 v39, 0xffff0000, v39
	v_add_f32_e32 v148, v116, v40
	v_add_f32_e32 v149, v117, v41
	v_lshlrev_b32_e32 v120, 16, v36
	v_and_b32_e32 v121, 0xffff0000, v36
	v_lshlrev_b32_e32 v36, 16, v37
	v_and_b32_e32 v37, 0xffff0000, v37
	v_add_f32_e32 v152, v148, v38
	v_add_f32_e32 v153, v149, v39
	v_exp_f32_e32 v144, v40
	v_exp_f32_e32 v145, v41
	v_add_f32_e32 v156, v152, v36
	v_add_f32_e32 v157, v153, v37
	v_exp_f32_e32 v40, v36
	v_exp_f32_e32 v41, v37
	v_mul_f32_e32 v36, v128, v122
	v_mul_f32_e32 v37, v129, v123
	v_exp_f32_e32 v146, v38
	v_exp_f32_e32 v147, v39
	v_mul_f32_e32 v48, v36, v48
	v_mul_f32_e32 v49, v37, v49
	v_mul_f32_e32 v36, v130, v36
	v_mul_f32_e32 v37, v131, v37
	ds_write_b64 v51, v[156:157]
	v_mul_f32_e32 v46, v36, v46
	v_mul_f32_e32 v47, v37, v47
	v_mul_f32_e32 v36, v136, v36
	v_mul_f32_e32 v37, v137, v37
	v_mul_f32_e32 v108, v122, v108
	v_mul_f32_e32 v109, v123, v109
	v_mul_f32_e32 v114, v36, v114
	v_mul_f32_e32 v115, v37, v115
	v_mul_f32_e32 v36, v138, v36
	v_mul_f32_e32 v37, v139, v37
	v_sub_f32_e32 v126, 1.0, v122
	v_sub_f32_e32 v127, 1.0, v123
	v_mul_f32_e32 v122, v36, v42
	v_mul_f32_e32 v123, v37, v43
	v_mul_f32_e32 v36, v144, v36
	v_mul_f32_e32 v37, v145, v37
	s_waitcnt lgkmcnt(0)
	s_barrier
	v_mul_f32_e32 v118, v36, v118
	v_mul_f32_e32 v119, v37, v119
	v_mul_f32_e32 v42, v146, v36
	v_mul_f32_e32 v43, v147, v37
	ds_read2st64_b64 v[36:39], v97 offset1:1
	v_lshlrev_b32_e32 v124, 16, v35
	v_and_b32_e32 v125, 0xffff0000, v35
	v_mul_f32_e32 v120, v42, v120
	v_mul_f32_e32 v121, v43, v121
	v_mul_f32_e32 v42, v40, v42
	v_mul_f32_e32 v43, v41, v43
	v_sub_f32_e32 v134, 1.0, v130
	v_sub_f32_e32 v135, 1.0, v131
	v_mul_f32_e32 v50, v42, v124
	v_mul_f32_e32 v51, v43, v125
	v_sub_f32_e32 v124, 1.0, v40
	v_sub_f32_e32 v125, 1.0, v41
	ds_read2st64_b64 v[40:43], v97 offset0:2 offset1:3
	s_waitcnt lgkmcnt(1)
	v_add_f32_e32 v35, 0, v36
	v_add_f32_e32 v36, 0, v37
	v_add_f32_e32 v35, v35, v38
	v_add_f32_e32 v37, 0, v38
	v_add_f32_e32 v38, 0, v39
	v_cndmask_b32_e64 v37, 0, v37, s[68:69]
	v_cndmask_b32_e64 v38, 0, v38, s[68:69]
	s_waitcnt lgkmcnt(0)
	v_add_f32_e32 v37, v40, v37
	v_add_f32_e32 v38, v41, v38
	v_cndmask_b32_e64 v37, 0, v37, s[70:71]
	v_cndmask_b32_e64 v38, 0, v38, s[70:71]
	v_add_f32_e32 v36, v36, v39
	v_add_f32_e32 v35, v35, v40
	v_add_f32_e32 v39, 0, v40
	v_add_f32_e32 v40, 0, v41
	v_add_f32_e32 v37, v42, v37
	v_add_f32_e32 v38, v43, v38
	v_cndmask_b32_e64 v37, 0, v37, s[72:73]
	v_cndmask_b32_e64 v105, 0, v38, s[72:73]
	v_add_f32_e32 v38, v39, v42
	v_add_f32_e32 v39, v40, v43
	v_sub_f32_e32 v130, v37, v38
	v_sub_f32_e32 v131, v105, v39
	v_sub_f32_e32 v140, 1.0, v136
	v_sub_f32_e32 v141, 1.0, v137
	v_sub_f32_e32 v136, v38, v37
	v_sub_f32_e32 v137, v39, v105
	v_exp_f32_e32 v38, v37
	v_exp_f32_e32 v130, v130
	v_exp_f32_e32 v131, v131
	v_exp_f32_e32 v39, v105
	v_add_f32_e32 v36, v36, v41
	v_exp_f32_e64 v40, -v156
	v_exp_f32_e64 v41, -v157
	v_exp_f32_e32 v136, v136
	v_exp_f32_e32 v137, v137
	v_sub_f32_e32 v150, 1.0, v144
	v_sub_f32_e32 v151, 1.0, v145
	v_add_f32_e32 v36, v36, v43
	v_mul_f32_e32 v144, v50, v38
	v_mul_f32_e32 v145, v51, v39
	v_mul_f32_e32 v50, v50, v130
	v_mul_f32_e32 v51, v51, v131
	v_sub_f32_e32 v142, 1.0, v138
	v_sub_f32_e32 v143, 1.0, v139
	v_sub_f32_e32 v139, v36, v105
	v_cvt_pk_bf16_f32 v105, v50, v51
	v_mul_f32_e32 v50, v124, v40
	v_mul_f32_e32 v51, v125, v41
	v_add_f32_e32 v35, v35, v42
	v_exp_f32_e64 v42, -v152
	v_exp_f32_e64 v43, -v153
	v_mul_f32_e32 v40, v50, v136
	v_mul_f32_e32 v41, v51, v137
	v_sub_f32_e32 v37, v35, v37
	v_cvt_pk_bf16_f32 v124, v40, v41
	v_mul_f32_e32 v40, v120, v38
	v_mul_f32_e32 v41, v121, v39
	v_exp_f32_e32 v138, v37
	v_cvt_pk_bf16_f32 v37, v144, v145
	v_cvt_pk_bf16_f32 v40, v40, v41
	v_add_u32_e32 v125, 0xa400, v18
	v_sub_f32_e32 v132, 1.0, v128
	v_sub_f32_e32 v133, 1.0, v129
	v_sub_f32_e32 v154, 1.0, v146
	v_sub_f32_e32 v155, 1.0, v147
	v_exp_f32_e64 v128, -v148
	v_exp_f32_e64 v129, -v149
	ds_write2_b32 v125, v37, v40 offset1:68
	v_mul_f32_e32 v40, v120, v130
	v_mul_f32_e32 v41, v121, v131
	v_mul_f32_e32 v42, v154, v42
	v_mul_f32_e32 v43, v155, v43
	v_cvt_pk_bf16_f32 v37, v40, v41
	v_add_u32_e32 v40, 0xc400, v18
	ds_write2_b32 v40, v105, v37 offset0:128 offset1:196
	v_mul_f32_e32 v40, v42, v136
	v_mul_f32_e32 v41, v43, v137
	v_add_u32_e32 v105, 0xe800, v18
	v_cvt_pk_bf16_f32 v37, v40, v41
	v_mul_f32_e32 v40, v118, v38
	v_mul_f32_e32 v41, v119, v39
	v_exp_f32_e64 v116, -v116
	v_exp_f32_e64 v117, -v117
	ds_write2_b32 v105, v124, v37 offset1:68
	v_cvt_pk_bf16_f32 v37, v40, v41
	v_mul_f32_e32 v40, v118, v130
	v_mul_f32_e32 v41, v119, v131
	v_mul_f32_e32 v118, v150, v128
	v_mul_f32_e32 v119, v151, v129
	v_cvt_pk_bf16_f32 v120, v40, v41
	v_mul_f32_e32 v40, v118, v136
	v_mul_f32_e32 v41, v119, v137
	v_exp_f32_e64 v44, -v44
	v_cvt_pk_bf16_f32 v121, v40, v41
	v_mul_f32_e32 v40, v122, v38
	v_mul_f32_e32 v41, v123, v39
	v_exp_f32_e64 v45, -v45
	v_cvt_pk_bf16_f32 v40, v40, v41
	ds_write2_b32 v125, v37, v40 offset0:136 offset1:204
	v_mul_f32_e32 v40, v122, v130
	v_mul_f32_e32 v41, v123, v131
	v_mul_f32_e32 v116, v142, v116
	v_mul_f32_e32 v117, v143, v117
	v_cvt_pk_bf16_f32 v37, v40, v41
	v_add_u32_e32 v122, 0xc800, v18
	v_mul_f32_e32 v40, v116, v136
	v_mul_f32_e32 v41, v117, v137
	ds_write2_b32 v122, v120, v37 offset0:8 offset1:76
	v_cvt_pk_bf16_f32 v37, v40, v41
	v_mul_f32_e32 v40, v114, v38
	v_mul_f32_e32 v41, v115, v39
	v_exp_f32_e64 v112, -v112
	v_exp_f32_e64 v113, -v113
	ds_write2_b32 v105, v121, v37 offset0:136 offset1:204
	v_cvt_pk_bf16_f32 v37, v40, v41
	v_mul_f32_e32 v40, v114, v130
	v_mul_f32_e32 v41, v115, v131
	v_mul_f32_e32 v44, v140, v44
	v_mul_f32_e32 v45, v141, v45
	v_cvt_pk_bf16_f32 v105, v40, v41
	v_mul_f32_e32 v40, v44, v136
	v_mul_f32_e32 v41, v45, v137
	v_add_u32_e32 v115, 0xa800, v18
	v_cvt_pk_bf16_f32 v114, v40, v41
	v_mul_f32_e32 v40, v46, v38
	v_mul_f32_e32 v41, v47, v39
	v_exp_f32_e64 v110, -v110
	v_cvt_pk_bf16_f32 v40, v40, v41
	ds_write2_b32 v115, v37, v40 offset0:16 offset1:84
	v_mul_f32_e32 v40, v46, v130
	v_mul_f32_e32 v41, v47, v131
	v_mul_f32_e32 v46, v134, v112
	v_mul_f32_e32 v47, v135, v113
	v_exp_f32_e64 v111, -v111
	v_exp_f32_e64 v106, -v106
	v_exp_f32_e64 v107, -v107
	v_cvt_pk_bf16_f32 v37, v40, v41
	v_mul_f32_e32 v40, v46, v136
	v_mul_f32_e32 v41, v47, v137
	ds_write2_b32 v122, v105, v37 offset0:144 offset1:212
	v_cvt_pk_bf16_f32 v37, v40, v41
	v_add_u32_e32 v105, 0xec00, v18
	v_mul_f32_e32 v40, v48, v38
	v_mul_f32_e32 v41, v49, v39
	v_mul_f32_e32 v38, v108, v38
	v_mul_f32_e32 v39, v109, v39
	ds_write2_b32 v105, v114, v37 offset0:16 offset1:84
	v_cvt_pk_bf16_f32 v37, v40, v41
	v_cvt_pk_bf16_f32 v38, v38, v39
	v_mul_f32_e32 v40, v48, v130
	v_mul_f32_e32 v41, v49, v131
	ds_write2_b32 v115, v37, v38 offset0:152 offset1:220
	v_mul_f32_e32 v38, v108, v130
	v_mul_f32_e32 v39, v109, v131
	v_cvt_pk_bf16_f32 v112, v40, v41
	v_mul_f32_e32 v48, v132, v110
	v_mul_f32_e32 v49, v133, v111
	v_cvt_pk_bf16_f32 v37, v38, v39
	v_add_u32_e32 v38, 0xcc00, v18
	v_mul_f32_e32 v106, v126, v106
	v_mul_f32_e32 v107, v127, v107
	v_mul_f32_e32 v40, v48, v136
	v_mul_f32_e32 v41, v49, v137
	ds_write2_b32 v38, v112, v37 offset0:24 offset1:92
	v_mul_f32_e32 v38, v106, v136
	v_mul_f32_e32 v39, v107, v137
	v_cvt_pk_bf16_f32 v40, v40, v41
	v_cvt_pk_bf16_f32 v37, v38, v39
	v_exp_f32_e32 v108, v139
	ds_write2_b32 v105, v40, v37 offset0:152 offset1:220
	v_mov_b32_e32 v38, v50
	v_mov_b32_e32 v39, v42
	v_mov_b32_e32 v40, v118
	v_mov_b32_e32 v41, v116
	v_mul_f32_e32 v38, v38, v138
	v_mul_f32_e32 v39, v39, v138
	v_mul_f32_e32 v40, v40, v138
	v_mul_f32_e32 v41, v41, v138
	v_cvt_pk_bf16_f32 v38, v38, v39
	v_cvt_pk_bf16_f32 v39, v40, v41
	v_mov_b32_e32 v40, v44
	v_mov_b32_e32 v41, v46
	v_mov_b32_e32 v110, v48
	v_mov_b32_e32 v111, v106
	v_mov_b32_e32 v42, v51
	v_mov_b32_e32 v116, v119
	v_mov_b32_e32 v46, v45
	v_mov_b32_e32 v106, v49
	v_mul_f32_e32 v40, v40, v138
	v_mul_f32_e32 v41, v41, v138
	v_mul_f32_e32 v110, v110, v138
	v_mul_f32_e32 v111, v111, v138
	v_mul_f32_e32 v42, v42, v108
	v_mul_f32_e32 v43, v43, v108
	v_mul_f32_e32 v50, v116, v108
	v_mul_f32_e32 v51, v117, v108
	v_mul_f32_e32 v44, v46, v108
	v_mul_f32_e32 v45, v47, v108
	v_mul_f32_e32 v46, v106, v108
	v_mul_f32_e32 v47, v107, v108
	v_cvt_pk_bf16_f32 v40, v40, v41
	v_cvt_pk_bf16_f32 v41, v110, v111
	v_cvt_pk_bf16_f32 v42, v42, v43
	v_cvt_pk_bf16_f32 v43, v50, v51
	v_cvt_pk_bf16_f32 v44, v44, v45
	v_cvt_pk_bf16_f32 v45, v46, v47
	s_and_b64 vcc, exec, s[74:75]
	ds_write_b128 v17, v[38:41]
	ds_write_b128 v17, v[42:45] offset:80
	s_cbranch_vccnz .LBB0_398
	v_exp_f32_e32 v38, v35
	v_exp_f32_e32 v39, v36
	ds_write_b64 v100, v[38:39]
	s_branch .LBB0_398

.LBB0_417:
	s_nop 6
	v_lshl_add_u32 v46, s95, 9, v106
	ds_read_b128 v[34:37], v46
	ds_read_b128 v[38:41], v46 offset:32
	ds_read_b128 v[42:45], v46 offset:64
	ds_read_b128 v[46:49], v46 offset:96
	v_add3_u32 v50, s86, v88, v110
	s_waitcnt lgkmcnt(3)
	v_mul_f32_e32 v20, v20, v36
	v_mul_f32_e32 v21, v21, v37
	s_waitcnt lgkmcnt(2)
	v_mul_f32_e32 v22, v22, v38
	v_mul_f32_e32 v23, v23, v39
	v_mul_f32_e32 v6, v6, v38
	v_mul_f32_e32 v7, v7, v39
	v_add3_u32 v38, s86, v107, v110
	s_waitcnt lgkmcnt(0)
	v_mul_f32_e32 v32, v32, v48
	v_mul_f32_e32 v33, v33, v49
	v_mul_f32_e32 v28, v28, v44
	v_mul_f32_e32 v29, v29, v45
	v_mul_f32_e32 v24, v24, v40
	v_mul_f32_e32 v25, v25, v41
	v_mul_f32_e32 v30, v30, v46
	v_mul_f32_e32 v31, v31, v47
	v_mul_f32_e32 v26, v26, v42
	v_mul_f32_e32 v27, v27, v43
	v_mul_f32_e32 v18, v18, v34
	v_mul_f32_e32 v19, v19, v35
	v_mul_f32_e32 v16, v16, v48
	v_mul_f32_e32 v17, v17, v49
	v_mul_f32_e32 v12, v12, v44
	v_mul_f32_e32 v13, v13, v45
	v_mul_f32_e32 v8, v8, v40
	v_mul_f32_e32 v9, v9, v41
	v_mul_f32_e32 v4, v4, v36
	v_mul_f32_e32 v5, v5, v37
	v_mul_f32_e32 v14, v14, v46
	v_mul_f32_e32 v15, v15, v47
	v_mul_f32_e32 v10, v10, v42
	v_mul_f32_e32 v11, v11, v43
	v_mul_f32_e32 v2, v2, v34
	v_mul_f32_e32 v3, v3, v35
	ds_read_b128 v[34:37], v38 offset:26112
	ds_read_b128 v[38:41], v38 offset:26144
	ds_read_b128 v[42:45], v50 offset:36352
	ds_read_b128 v[46:49], v50 offset:36384
	s_waitcnt lgkmcnt(1)
	v_mfma_f32_32x32x16_bf16 v[18:33], v[34:37], v[42:45], v[18:33]
	ds_read_b128 v[42:45], v50 offset:38912
	s_add_u32 s74, s74, 0x8000
	s_addc_u32 s75, s75, 0
	s_add_i32 s1, s1, 1
	s_cmp_lg_u32 s74, 0x400000
	s_waitcnt lgkmcnt(0)
	v_mfma_f32_32x32x16_bf16 v[2:17], v[34:37], v[42:45], v[2:17]
	ds_read_b128 v[34:37], v50 offset:38944
	v_add_u32_e32 v42, 0x2000, v108
	v_mfma_f32_32x32x16_bf16 v[18:33], v[38:41], v[46:49], v[18:33]
	s_waitcnt lgkmcnt(0)
	v_mfma_f32_32x32x16_bf16 v[2:17], v[38:41], v[34:37], v[2:17]
	s_nop 9
	v_cvt_pk_bf16_f32 v34, v18, v19
	v_cvt_pk_bf16_f32 v35, v20, v21
	v_cvt_pk_bf16_f32 v38, v22, v23
	v_cvt_pk_bf16_f32 v39, v24, v25
	ds_write2_b64 v108, v[34:35], v[38:39] offset1:2
	v_cvt_pk_bf16_f32 v34, v26, v27
	v_cvt_pk_bf16_f32 v35, v28, v29
	v_cvt_pk_bf16_f32 v36, v2, v3
	v_cvt_pk_bf16_f32 v37, v4, v5
	v_cvt_pk_bf16_f32 v40, v6, v7
	v_cvt_pk_bf16_f32 v41, v8, v9
	v_cvt_pk_bf16_f32 v38, v30, v31
	v_cvt_pk_bf16_f32 v39, v32, v33
	ds_write2_b64 v42, v[36:37], v[40:41] offset0:64 offset1:66
	v_cvt_pk_bf16_f32 v36, v10, v11
	v_cvt_pk_bf16_f32 v37, v12, v13
	v_cvt_pk_bf16_f32 v40, v14, v15
	v_cvt_pk_bf16_f32 v41, v16, v17
	ds_write2_b64 v108, v[34:35], v[38:39] offset0:4 offset1:6
	ds_write2_b64 v42, v[36:37], v[40:41] offset0:68 offset1:70
	s_waitcnt lgkmcnt(0)
	s_barrier
	s_cbranch_scc0 .LBB0_426

.Lmy_sc_s86_wb0:
	v_lshlrev_b32_e32 v34, 1, v87
	v_add3_u32 v111, s86, v34, v110
	ds_read_b128 v[160:163], v111 offset:17408
	ds_read_b128 v[164:167], v111 offset:8704
	ds_read_b128 v[168:171], v111 offset:17440
	ds_read_b128 v[172:175], v111 offset:8736
	ds_read_b128 v[176:179], v111 offset:17472
	ds_read_b128 v[180:183], v111 offset:8768
	ds_read_b128 v[184:187], v111 offset:17504
	ds_read_b128 v[188:191], v111 offset:8800
	ds_read_b128 v[192:195], v111 offset:17536
	ds_read_b128 v[196:199], v111 offset:8832
	ds_read_b128 v[200:203], v111 offset:17568
	ds_read_b128 v[204:207], v111 offset:8864
	ds_read_b128 v[208:211], v111 offset:17600
	ds_read_b128 v[212:215], v111 offset:8896
	s_waitcnt lgkmcnt(12)
	v_mfma_f32_32x32x16_bf16 v[50:65], v[160:163], v[164:167], 0
	ds_read_b128 v[216:219], v111 offset:17632
	ds_read_b128 v[220:223], v111 offset:8928
	s_waitcnt lgkmcnt(12)
	v_mfma_f32_32x32x16_bf16 v[34:49], v[168:171], v[172:175], 0
	s_waitcnt lgkmcnt(10)
	v_mfma_f32_32x32x16_bf16 v[50:65], v[176:179], v[180:183], v[50:65]
	s_waitcnt lgkmcnt(8)
	v_mfma_f32_32x32x16_bf16 v[34:49], v[184:187], v[188:191], v[34:49]
	s_waitcnt lgkmcnt(6)
	v_mfma_f32_32x32x16_bf16 v[50:65], v[192:195], v[196:199], v[50:65]
	s_waitcnt lgkmcnt(4)
	v_mfma_f32_32x32x16_bf16 v[34:49], v[200:203], v[204:207], v[34:49]
	s_waitcnt lgkmcnt(2)
	v_mfma_f32_32x32x16_bf16 v[50:65], v[208:211], v[212:215], v[50:65]
	s_waitcnt lgkmcnt(0)
	v_mfma_f32_32x32x16_bf16 v[34:49], v[216:219], v[220:223], v[34:49]
	s_nop 11
	v_add_f32_e32 v111, v50, v34
	v_add_f32_e32 v112, v51, v35
	v_cndmask_b32_e64 v111, v111, 0, s[38:39]
	v_cndmask_b32_e64 v126, 0, v112, s[4:5]
	v_add_f32_e32 v124, v52, v36
	v_add_f32_e32 v125, v53, v37
	v_cvt_pk_bf16_f32 v126, v111, v126
	v_cvt_pk_bf16_f32 v111, v124, v125
	v_cndmask_b32_e64 v124, v111, 0, s[42:43]
	v_lshrrev_b32_e32 v111, 16, v111
	v_cndmask_b32_e64 v111, v111, 0, s[40:41]
	v_add_f32_e32 v122, v54, v38
	v_add_f32_e32 v123, v55, v39
	v_perm_b32 v127, v111, v124, s3
	v_add_u32_e32 v111, v89, v92
	ds_write_b64 v111, v[126:127]
	v_cvt_pk_bf16_f32 v111, v122, v123
	v_cndmask_b32_e64 v122, v111, 0, s[46:47]
	v_lshrrev_b32_e32 v111, 16, v111
	v_add_f32_e32 v120, v56, v40
	v_add_f32_e32 v121, v57, v41
	v_cndmask_b32_e64 v111, v111, 0, s[44:45]
	v_perm_b32 v122, v111, v122, s3
	v_cvt_pk_bf16_f32 v111, v120, v121
	v_cndmask_b32_e64 v120, v111, 0, s[50:51]
	v_lshrrev_b32_e32 v111, 16, v111
	v_add_f32_e32 v118, v58, v42
	v_add_f32_e32 v119, v59, v43
	v_cndmask_b32_e64 v111, v111, 0, s[48:49]
	v_perm_b32 v123, v111, v120, s3
	v_cvt_pk_bf16_f32 v111, v118, v119
	v_cndmask_b32_e64 v118, v111, 0, s[54:55]
	v_lshrrev_b32_e32 v111, 16, v111
	v_add_f32_e32 v116, v60, v44
	v_add_f32_e32 v117, v61, v45
	v_cndmask_b32_e64 v111, v111, 0, s[52:53]
	v_perm_b32 v118, v111, v118, s3
	v_cvt_pk_bf16_f32 v111, v116, v117
	v_cndmask_b32_e64 v116, v111, 0, s[58:59]
	v_lshrrev_b32_e32 v111, 16, v111
	v_add_f32_e32 v114, v62, v46
	v_add_f32_e32 v115, v63, v47
	v_cndmask_b32_e64 v111, v111, 0, s[56:57]
	v_perm_b32 v119, v111, v116, s3
	v_cvt_pk_bf16_f32 v111, v114, v115
	v_cndmask_b32_e64 v114, v111, 0, s[62:63]
	v_lshrrev_b32_e32 v111, 16, v111
	v_add_f32_e32 v112, v64, v48
	v_add_f32_e32 v113, v65, v49
	v_cndmask_b32_e64 v111, v111, 0, s[60:61]
	v_perm_b32 v114, v111, v114, s3
	v_cvt_pk_bf16_f32 v111, v112, v113
	v_cndmask_b32_e64 v112, v111, 0, s[66:67]
	v_lshrrev_b32_e32 v111, 16, v111
	v_cndmask_b32_e64 v111, v111, 0, s[64:65]
	v_perm_b32 v115, v111, v112, s3
	ds_write_b64 v93, v[122:123]
	ds_write_b64 v94, v[118:119]
	ds_write_b64 v95, v[114:115]

.LBB0_432:
	v_lshlrev_b32_e32 v106, 16, v105
	v_and_b32_e32 v107, 0xffff0000, v105
	v_lshlrev_b32_e32 v110, 16, v81
	v_and_b32_e32 v111, 0xffff0000, v81
	v_lshlrev_b32_e32 v108, 16, v64
	v_and_b32_e32 v109, 0xffff0000, v64
	v_lshlrev_b32_e32 v64, 16, v65
	v_and_b32_e32 v65, 0xffff0000, v65
	v_exp_f32_e32 v124, v106
	v_exp_f32_e32 v125, v107
	v_exp_f32_e32 v126, v110
	v_exp_f32_e32 v127, v111
	v_lshlrev_b32_e32 v116, 16, v62
	v_and_b32_e32 v117, 0xffff0000, v62
	v_add_f32_e32 v106, 0, v106
	v_add_f32_e32 v107, 0, v107
	v_exp_f32_e32 v130, v64
	v_exp_f32_e32 v131, v65
	v_lshlrev_b32_e32 v120, 16, v80
	v_and_b32_e32 v121, 0xffff0000, v80
	v_add_f32_e32 v110, v106, v110
	v_add_f32_e32 v111, v107, v111
	v_exp_f32_e32 v132, v116
	v_exp_f32_e32 v133, v117
	v_lshlrev_b32_e32 v62, 16, v63
	v_and_b32_e32 v63, 0xffff0000, v63
	v_add_f32_e32 v64, v110, v64
	v_add_f32_e32 v65, v111, v65
	v_exp_f32_e32 v134, v120
	v_exp_f32_e32 v135, v121
	v_lshlrev_b32_e32 v112, 16, v61
	v_and_b32_e32 v113, 0xffff0000, v61
	v_lshlrev_b32_e32 v114, 16, v57
	v_and_b32_e32 v115, 0xffff0000, v57
	v_lshlrev_b32_e32 v122, 16, v56
	v_and_b32_e32 v123, 0xffff0000, v56
	v_lshlrev_b32_e32 v56, 16, v60
	v_and_b32_e32 v57, 0xffff0000, v60
	v_mul_f32_e32 v108, v124, v108
	v_mul_f32_e32 v109, v125, v109
	v_sub_f32_e32 v128, 1.0, v124
	v_sub_f32_e32 v129, 1.0, v125
	v_mul_f32_e32 v124, v124, v126
	v_mul_f32_e32 v125, v125, v127
	v_add_f32_e32 v116, v64, v116
	v_add_f32_e32 v117, v65, v117
	v_exp_f32_e32 v136, v62
	v_exp_f32_e32 v137, v63
	v_mul_f32_e32 v112, v124, v112
	v_mul_f32_e32 v113, v125, v113
	v_mul_f32_e32 v124, v124, v130
	v_mul_f32_e32 v125, v125, v131
	v_add_f32_e32 v120, v116, v120
	v_add_f32_e32 v121, v117, v121
	v_exp_f32_e32 v138, v56
	v_exp_f32_e32 v139, v57
	v_lshlrev_b32_e32 v118, 16, v55
	v_and_b32_e32 v119, 0xffff0000, v55
	v_mul_f32_e32 v114, v124, v114
	v_mul_f32_e32 v115, v125, v115
	v_mul_f32_e32 v124, v124, v132
	v_mul_f32_e32 v125, v125, v133
	v_add_f32_e32 v62, v120, v62
	v_add_f32_e32 v63, v121, v63
	v_lshlrev_b32_e32 v80, 16, v59
	v_and_b32_e32 v81, 0xffff0000, v59
	v_lshlrev_b32_e32 v60, 16, v54
	v_and_b32_e32 v61, 0xffff0000, v54
	v_lshlrev_b32_e32 v54, 16, v58
	v_and_b32_e32 v55, 0xffff0000, v58
	v_mul_f32_e32 v118, v124, v118
	v_mul_f32_e32 v119, v125, v119
	v_mul_f32_e32 v124, v124, v134
	v_mul_f32_e32 v125, v125, v135
	v_add_f32_e32 v140, v62, v56
	v_add_f32_e32 v141, v63, v57
	v_lshlrev_b32_e32 v58, 16, v53
	v_and_b32_e32 v59, 0xffff0000, v53
	v_mul_f32_e32 v80, v124, v80
	v_mul_f32_e32 v81, v125, v81
	v_mul_f32_e32 v124, v124, v136
	v_mul_f32_e32 v125, v125, v137
	v_add_f32_e32 v144, v140, v54
	v_add_f32_e32 v145, v141, v55
	v_add_u32_e32 v53, s86, v97
	v_mul_f32_e32 v122, v124, v122
	v_mul_f32_e32 v123, v125, v123
	v_mul_f32_e32 v124, v124, v138
	v_mul_f32_e32 v125, v125, v139
	ds_write_b64 v53, v[144:145]
	v_mul_f32_e32 v142, v124, v60
	v_mul_f32_e32 v143, v125, v61
	v_exp_f32_e32 v60, v54
	v_exp_f32_e32 v61, v55
	s_waitcnt lgkmcnt(0)
	s_barrier
	ds_read2st64_b64 v[54:57], v97 offset1:1
	v_mul_f32_e32 v124, v124, v60
	v_mul_f32_e32 v125, v125, v61
	v_sub_f32_e32 v146, 1.0, v60
	v_sub_f32_e32 v147, 1.0, v61
	v_mul_f32_e32 v124, v124, v58
	v_mul_f32_e32 v125, v125, v59
	ds_read2st64_b64 v[58:61], v97 offset0:2 offset1:3
	s_waitcnt lgkmcnt(1)
	v_add_f32_e32 v54, 0, v54
	v_add_f32_e32 v55, 0, v55
	v_cndmask_b32_e64 v68, v55, 0, s[0:1]
	v_cndmask_b32_e64 v105, v54, 0, s[0:1]
	v_add_f32_e32 v148, v54, v56
	v_add_f32_e32 v149, v55, v57
	v_add_f32_e32 v54, v56, v105
	v_add_f32_e32 v55, v57, v68
	v_cndmask_b32_e64 v55, v68, v55, s[68:69]
	v_cndmask_b32_e64 v54, v105, v54, s[68:69]
	s_waitcnt lgkmcnt(0)
	v_add_f32_e32 v56, v148, v58
	v_add_f32_e32 v57, v149, v59
	v_add_f32_e32 v58, v58, v54
	v_add_f32_e32 v59, v59, v55
	v_cndmask_b32_e64 v68, v55, v59, s[70:71]
	v_cndmask_b32_e64 v58, v54, v58, s[70:71]
	v_add_f32_e32 v54, v56, v60
	v_add_f32_e32 v55, v57, v61
	v_sub_f32_e32 v57, v58, v148
	v_sub_f32_e32 v105, v68, v149
	v_sub_f32_e32 v148, v148, v58
	v_exp_f32_e32 v56, v58
	v_sub_f32_e32 v150, v54, v58
	v_exp_f32_e64 v58, -v106
	v_exp_f32_e64 v59, -v107
	v_exp_f32_e64 v106, -v116
	v_exp_f32_e64 v107, -v117
	v_exp_f32_e64 v116, -v140
	v_exp_f32_e64 v117, -v141
	v_exp_f32_e32 v140, v57
	v_exp_f32_e32 v141, v105
	v_exp_f32_e32 v57, v68
	v_sub_f32_e32 v149, v149, v68
	v_exp_f32_e64 v60, -v110
	v_exp_f32_e64 v61, -v111
	v_exp_f32_e64 v110, -v120
	v_exp_f32_e64 v111, -v121
	v_exp_f32_e64 v120, -v144
	v_exp_f32_e64 v121, -v145
	v_exp_f32_e32 v144, v148
	v_exp_f32_e32 v145, v149
	v_mul_f32_e32 v148, v108, v56
	v_mul_f32_e32 v149, v109, v57
	v_mul_f32_e32 v108, v108, v140
	v_mul_f32_e32 v109, v109, v141
	v_cvt_pk_bf16_f32 v105, v148, v149
	v_cvt_pk_bf16_f32 v148, v108, v109
	v_mul_f32_e32 v108, v128, v58
	v_mul_f32_e32 v109, v129, v59
	v_sub_f32_e32 v126, 1.0, v126
	v_sub_f32_e32 v127, 1.0, v127
	v_mul_f32_e32 v58, v108, v144
	v_mul_f32_e32 v59, v109, v145
	v_exp_f32_e64 v64, -v64
	v_cvt_pk_bf16_f32 v128, v58, v59
	v_mul_f32_e32 v58, v112, v56
	v_mul_f32_e32 v59, v113, v57
	v_exp_f32_e64 v65, -v65
	v_cvt_pk_bf16_f32 v58, v58, v59
	ds_write2_b32 v20, v105, v58 offset1:68
	v_mul_f32_e32 v58, v112, v140
	v_mul_f32_e32 v59, v113, v141
	v_mul_f32_e32 v60, v126, v60
	v_mul_f32_e32 v61, v127, v61
	v_cvt_pk_bf16_f32 v58, v58, v59
	v_add_u32_e32 v59, 0x2000, v20
	ds_write2_b32 v59, v148, v58 offset0:128 offset1:196
	v_mul_f32_e32 v58, v60, v144
	v_mul_f32_e32 v59, v61, v145
	v_add_u32_e32 v105, 0x4400, v20
	v_cvt_pk_bf16_f32 v58, v58, v59
	v_sub_f32_e32 v130, 1.0, v130
	v_sub_f32_e32 v131, 1.0, v131
	ds_write2_b32 v105, v128, v58 offset1:68
	v_mul_f32_e32 v58, v114, v56
	v_mul_f32_e32 v59, v115, v57
	v_mul_f32_e32 v64, v130, v64
	v_mul_f32_e32 v65, v131, v65
	v_cvt_pk_bf16_f32 v112, v58, v59
	v_mul_f32_e32 v58, v114, v140
	v_mul_f32_e32 v59, v115, v141
	v_sub_f32_e32 v132, 1.0, v132
	v_sub_f32_e32 v133, 1.0, v133
	v_cvt_pk_bf16_f32 v113, v58, v59
	v_mul_f32_e32 v58, v64, v144
	v_mul_f32_e32 v59, v65, v145
	v_mul_f32_e32 v106, v132, v106
	v_mul_f32_e32 v107, v133, v107
	v_cvt_pk_bf16_f32 v114, v58, v59
	v_mul_f32_e32 v58, v118, v56
	v_mul_f32_e32 v59, v119, v57
	v_sub_f32_e32 v134, 1.0, v134
	v_sub_f32_e32 v135, 1.0, v135
	v_cvt_pk_bf16_f32 v58, v58, v59
	ds_write2_b32 v20, v112, v58 offset0:136 offset1:204
	v_mul_f32_e32 v58, v118, v140
	v_mul_f32_e32 v59, v119, v141
	v_add_u32_e32 v112, 0x2400, v20
	v_cvt_pk_bf16_f32 v58, v58, v59
	ds_write2_b32 v112, v113, v58 offset0:8 offset1:76
	v_mul_f32_e32 v58, v106, v144
	v_mul_f32_e32 v59, v107, v145
	v_exp_f32_e64 v62, -v62
	v_cvt_pk_bf16_f32 v58, v58, v59
	ds_write2_b32 v105, v114, v58 offset0:136 offset1:204
	v_mul_f32_e32 v58, v80, v56
	v_mul_f32_e32 v59, v81, v57
	v_exp_f32_e64 v63, -v63
	v_cvt_pk_bf16_f32 v105, v58, v59
	v_mul_f32_e32 v58, v80, v140
	v_mul_f32_e32 v59, v81, v141
	v_mul_f32_e32 v80, v134, v110
	v_mul_f32_e32 v81, v135, v111
	v_cvt_pk_bf16_f32 v113, v58, v59
	v_mul_f32_e32 v58, v80, v144
	v_mul_f32_e32 v59, v81, v145
	v_add_u32_e32 v114, 0x400, v20
	v_cvt_pk_bf16_f32 v110, v58, v59
	v_mul_f32_e32 v58, v122, v56
	v_mul_f32_e32 v59, v123, v57
	v_sub_f32_e32 v136, 1.0, v136
	v_sub_f32_e32 v137, 1.0, v137
	v_cvt_pk_bf16_f32 v58, v58, v59
	ds_write2_b32 v114, v105, v58 offset0:16 offset1:84
	v_mul_f32_e32 v58, v122, v140
	v_mul_f32_e32 v59, v123, v141
	v_mul_f32_e32 v62, v136, v62
	v_mul_f32_e32 v63, v137, v63
	v_cvt_pk_bf16_f32 v58, v58, v59
	ds_write2_b32 v112, v113, v58 offset0:144 offset1:212
	v_mul_f32_e32 v58, v62, v144
	v_mul_f32_e32 v59, v63, v145
	v_add_u32_e32 v105, 0x4800, v20
	v_cvt_pk_bf16_f32 v58, v58, v59
	ds_write2_b32 v105, v110, v58 offset0:16 offset1:84
	v_mul_f32_e32 v58, v142, v56
	v_mul_f32_e32 v59, v143, v57
	v_mul_f32_e32 v56, v124, v56
	v_mul_f32_e32 v57, v125, v57
	v_cvt_pk_bf16_f32 v112, v58, v59
	v_cvt_pk_bf16_f32 v56, v56, v57
	v_mul_f32_e32 v58, v142, v140
	v_mul_f32_e32 v59, v143, v141
	ds_write2_b32 v114, v112, v56 offset0:152 offset1:220
	v_mul_f32_e32 v56, v124, v140
	v_mul_f32_e32 v57, v125, v141
	v_sub_f32_e32 v138, 1.0, v138
	v_sub_f32_e32 v139, 1.0, v139
	v_cvt_pk_bf16_f32 v113, v58, v59
	v_cvt_pk_bf16_f32 v56, v56, v57
	v_add_u32_e32 v57, 0x2800, v20
	v_sub_f32_e32 v151, v55, v68
	v_exp_f32_e32 v68, v150
	v_mul_f32_e32 v110, v138, v116
	v_mul_f32_e32 v111, v139, v117
	ds_write2_b32 v57, v113, v56 offset0:24 offset1:92
	v_mul_f32_e32 v112, v146, v120
	v_mul_f32_e32 v113, v147, v121
	v_mul_f32_e32 v58, v110, v144
	v_mul_f32_e32 v59, v111, v145
	v_mul_f32_e32 v56, v112, v144
	v_mul_f32_e32 v57, v113, v145
	v_cvt_pk_bf16_f32 v58, v58, v59
	v_cvt_pk_bf16_f32 v56, v56, v57
	ds_write2_b32 v105, v58, v56 offset0:152 offset1:220
	v_exp_f32_e32 v114, v151
	v_mov_b32_e32 v56, v108
	v_mov_b32_e32 v57, v60
	v_mov_b32_e32 v58, v64
	v_mov_b32_e32 v59, v106
	v_mul_f32_e32 v56, v56, v68
	v_mul_f32_e32 v57, v57, v68
	v_mul_f32_e32 v58, v58, v68
	v_mul_f32_e32 v59, v59, v68
	v_cvt_pk_bf16_f32 v56, v56, v57
	v_cvt_pk_bf16_f32 v57, v58, v59
	v_mov_b32_e32 v58, v80
	v_mov_b32_e32 v59, v62
	v_mov_b32_e32 v116, v110
	v_mov_b32_e32 v117, v112
	v_mul_f32_e32 v58, v58, v68
	v_mul_f32_e32 v59, v59, v68
	v_mul_f32_e32 v116, v116, v68
	v_mul_f32_e32 v117, v117, v68
	v_mov_b32_e32 v60, v109
	v_mov_b32_e32 v106, v65
	v_cvt_pk_bf16_f32 v58, v58, v59
	v_cvt_pk_bf16_f32 v59, v116, v117
	v_mul_f32_e32 v60, v60, v114
	v_mul_f32_e32 v61, v61, v114
	v_mul_f32_e32 v64, v106, v114
	v_mul_f32_e32 v65, v107, v114
	v_mov_b32_e32 v62, v81
	v_mov_b32_e32 v112, v111
	v_cvt_pk_bf16_f32 v60, v60, v61
	v_cvt_pk_bf16_f32 v61, v64, v65
	v_mul_f32_e32 v62, v62, v114
	v_mul_f32_e32 v63, v63, v114
	v_mul_f32_e32 v64, v112, v114
	v_mul_f32_e32 v65, v113, v114
	ds_write_b128 v18, v[56:59] offset:26112
	v_cndmask_b32_e64 v56, 0, 1, s[0:1]
	v_cvt_pk_bf16_f32 v62, v62, v63
	v_cvt_pk_bf16_f32 v63, v64, v65
	v_cmp_ne_u32_e64 s[72:73], 1, v56
	s_andn2_b64 vcc, exec, s[0:1]
	ds_write_b128 v18, v[60:63] offset:26192
	s_cbranch_vccnz .LBB0_434
	v_exp_f32_e32 v54, v54
	v_exp_f32_e32 v55, v55
	ds_write_b64 v98, v[54:55]

.LBB0_436:
	v_lshlrev_b32_e32 v14, 16, v51
	v_and_b32_e32 v15, 0xffff0000, v51
	v_lshlrev_b32_e32 v106, 16, v50
	v_and_b32_e32 v107, 0xffff0000, v50
	v_exp_f32_e32 v120, v14
	v_exp_f32_e32 v121, v15
	v_add_f32_e32 v122, 0, v14
	v_add_f32_e32 v123, 0, v15
	v_exp_f32_e32 v14, v106
	v_exp_f32_e32 v15, v107
	v_lshlrev_b32_e32 v16, 16, v52
	v_and_b32_e32 v17, 0xffff0000, v52
	v_lshlrev_b32_e32 v108, 16, v49
	v_and_b32_e32 v109, 0xffff0000, v49
	v_mul_f32_e32 v124, v120, v16
	v_mul_f32_e32 v125, v121, v17
	v_sub_f32_e32 v126, 1.0, v120
	v_sub_f32_e32 v127, 1.0, v121
	v_mul_f32_e32 v16, v120, v14
	v_mul_f32_e32 v17, v121, v15
	v_exp_f32_e32 v120, v108
	v_exp_f32_e32 v121, v109
	v_lshlrev_b32_e32 v50, 16, v47
	v_and_b32_e32 v51, 0xffff0000, v47
	v_lshlrev_b32_e32 v112, 16, v48
	v_and_b32_e32 v113, 0xffff0000, v48
	v_add_f32_e32 v106, v122, v106
	v_add_f32_e32 v107, v123, v107
	v_mul_f32_e32 v50, v16, v50
	v_mul_f32_e32 v51, v17, v51
	v_sub_f32_e32 v128, 1.0, v14
	v_sub_f32_e32 v129, 1.0, v15
	v_mul_f32_e32 v14, v16, v120
	v_mul_f32_e32 v15, v17, v121
	v_exp_f32_e32 v16, v112
	v_exp_f32_e32 v17, v113
	v_add_f32_e32 v108, v106, v108
	v_add_f32_e32 v109, v107, v109
	v_lshlrev_b32_e32 v114, 16, v46
	v_and_b32_e32 v115, 0xffff0000, v46
	v_add_f32_e32 v112, v108, v112
	v_add_f32_e32 v113, v109, v113
	v_lshlrev_b32_e32 v110, 16, v45
	v_and_b32_e32 v111, 0xffff0000, v45
	v_lshlrev_b32_e32 v116, 16, v44
	v_and_b32_e32 v117, 0xffff0000, v44
	v_exp_f32_e32 v130, v114
	v_exp_f32_e32 v131, v115
	v_add_f32_e32 v114, v112, v114
	v_add_f32_e32 v115, v113, v115
	v_lshlrev_b32_e32 v118, 16, v42
	v_and_b32_e32 v119, 0xffff0000, v42
	v_mul_f32_e32 v110, v14, v110
	v_mul_f32_e32 v111, v15, v111
	v_mul_f32_e32 v14, v14, v16
	v_mul_f32_e32 v15, v15, v17
	v_sub_f32_e32 v132, 1.0, v16
	v_sub_f32_e32 v133, 1.0, v17
	v_exp_f32_e32 v16, v116
	v_exp_f32_e32 v17, v117
	v_add_f32_e32 v116, v114, v116
	v_add_f32_e32 v117, v115, v117
	v_lshlrev_b32_e32 v48, 16, v43
	v_and_b32_e32 v49, 0xffff0000, v43
	v_lshlrev_b32_e32 v44, 16, v39
	v_and_b32_e32 v45, 0xffff0000, v39
	v_lshlrev_b32_e32 v42, 16, v38
	v_and_b32_e32 v43, 0xffff0000, v38
	v_lshlrev_b32_e32 v38, 16, v40
	v_and_b32_e32 v39, 0xffff0000, v40
	v_exp_f32_e32 v134, v118
	v_exp_f32_e32 v135, v119
	v_add_f32_e32 v118, v116, v118
	v_add_f32_e32 v119, v117, v119
	v_lshlrev_b32_e32 v46, 16, v41
	v_add_f32_e32 v140, v118, v38
	v_add_f32_e32 v141, v119, v39
	v_and_b32_e32 v47, 0xffff0000, v41
	v_mul_f32_e32 v48, v14, v48
	v_mul_f32_e32 v49, v15, v49
	v_mul_f32_e32 v14, v14, v130
	v_mul_f32_e32 v15, v15, v131
	ds_write_b64 v53, v[140:141]
	v_mul_f32_e32 v46, v14, v46
	v_mul_f32_e32 v47, v15, v47
	v_mul_f32_e32 v14, v14, v16
	v_mul_f32_e32 v15, v15, v17
	v_exp_f32_e32 v38, v38
	v_exp_f32_e32 v39, v39
	s_waitcnt lgkmcnt(0)
	s_barrier
	v_mul_f32_e32 v44, v14, v44
	v_mul_f32_e32 v45, v15, v45
	v_sub_f32_e32 v136, 1.0, v16
	v_sub_f32_e32 v137, 1.0, v17
	v_mul_f32_e32 v138, v14, v134
	v_mul_f32_e32 v139, v15, v135
	ds_read2st64_b64 v[14:17], v97 offset1:1
	v_lshlrev_b32_e32 v40, 16, v37
	v_and_b32_e32 v41, 0xffff0000, v37
	v_mul_f32_e32 v52, v138, v38
	v_mul_f32_e32 v53, v139, v39
	v_mul_f32_e32 v42, v138, v42
	v_mul_f32_e32 v43, v139, v43
	v_mul_f32_e32 v52, v52, v40
	v_mul_f32_e32 v53, v53, v41
	v_sub_f32_e32 v138, 1.0, v38
	v_sub_f32_e32 v139, 1.0, v39
	ds_read2st64_b64 v[38:41], v97 offset0:2 offset1:3
	s_waitcnt lgkmcnt(1)
	v_add_f32_e32 v14, 0, v14
	v_add_f32_e32 v15, 0, v15
	v_cndmask_b32_e64 v37, v14, 0, s[0:1]
	v_cndmask_b32_e64 v142, v15, 0, s[0:1]
	v_add_f32_e32 v143, v14, v16
	v_add_f32_e32 v144, v15, v17
	v_add_f32_e32 v14, v16, v37
	v_add_f32_e32 v15, v17, v142
	v_cndmask_b32_e64 v14, v37, v14, s[68:69]
	v_cndmask_b32_e64 v15, v142, v15, s[68:69]
	s_waitcnt lgkmcnt(0)
	v_add_f32_e32 v16, v143, v38
	v_add_f32_e32 v37, v38, v14
	v_add_f32_e32 v38, v39, v15
	v_add_f32_e32 v17, v144, v39
	v_cndmask_b32_e64 v37, v14, v37, s[70:71]
	v_cndmask_b32_e64 v142, v15, v38, s[70:71]
	v_add_f32_e32 v15, v17, v41
	v_sub_f32_e32 v17, v37, v143
	v_sub_f32_e32 v145, v142, v144
	v_add_f32_e32 v14, v16, v40
	v_exp_f32_e32 v16, v37
	v_exp_f32_e64 v38, -v122
	v_exp_f32_e64 v39, -v123
	v_exp_f32_e32 v122, v17
	v_exp_f32_e32 v123, v145
	v_exp_f32_e32 v17, v142
	v_sub_f32_e32 v143, v143, v37
	v_sub_f32_e32 v144, v144, v142
	v_exp_f32_e64 v40, -v106
	v_exp_f32_e64 v41, -v107
	v_exp_f32_e64 v106, -v108
	v_exp_f32_e64 v107, -v109
	v_exp_f32_e64 v108, -v112
	v_exp_f32_e64 v109, -v113
	v_exp_f32_e64 v112, -v114
	v_exp_f32_e64 v113, -v115
	v_exp_f32_e64 v114, -v116
	v_exp_f32_e64 v115, -v117
	v_exp_f32_e64 v116, -v118
	v_exp_f32_e64 v117, -v119
	v_exp_f32_e64 v118, -v140
	v_exp_f32_e64 v119, -v141
	v_exp_f32_e32 v140, v143
	v_exp_f32_e32 v141, v144
	v_mul_f32_e32 v144, v124, v16
	v_mul_f32_e32 v145, v125, v17
	v_mul_f32_e32 v124, v124, v122
	v_mul_f32_e32 v125, v125, v123
	v_sub_f32_e32 v37, v14, v37
	v_cvt_pk_bf16_f32 v143, v124, v125
	v_mul_f32_e32 v124, v126, v38
	v_mul_f32_e32 v125, v127, v39
	v_sub_f32_e32 v146, v15, v142
	v_mul_f32_e32 v38, v124, v140
	v_mul_f32_e32 v39, v125, v141
	v_exp_f32_e32 v142, v37
	v_cvt_pk_bf16_f32 v126, v38, v39
	v_mul_f32_e32 v38, v50, v16
	v_mul_f32_e32 v39, v51, v17
	v_cvt_pk_bf16_f32 v37, v144, v145
	v_cvt_pk_bf16_f32 v38, v38, v39
	v_add_u32_e32 v127, 0xa400, v20
	ds_write2_b32 v127, v37, v38 offset1:68
	v_mul_f32_e32 v38, v50, v122
	v_mul_f32_e32 v39, v51, v123
	v_mul_f32_e32 v50, v128, v40
	v_mul_f32_e32 v51, v129, v41
	v_cvt_pk_bf16_f32 v37, v38, v39
	v_add_u32_e32 v38, 0xc400, v20
	ds_write2_b32 v38, v143, v37 offset0:128 offset1:196
	v_mul_f32_e32 v38, v50, v140
	v_mul_f32_e32 v39, v51, v141
	v_sub_f32_e32 v120, 1.0, v120
	v_sub_f32_e32 v121, 1.0, v121
	v_cvt_pk_bf16_f32 v37, v38, v39
	v_add_u32_e32 v40, 0xe800, v20
	v_mul_f32_e32 v38, v110, v16
	v_mul_f32_e32 v39, v111, v17
	ds_write2_b32 v40, v126, v37 offset1:68
	v_cvt_pk_bf16_f32 v37, v38, v39
	v_mul_f32_e32 v38, v110, v122
	v_mul_f32_e32 v39, v111, v123
	v_mul_f32_e32 v106, v120, v106
	v_mul_f32_e32 v107, v121, v107
	v_cvt_pk_bf16_f32 v41, v38, v39
	v_mul_f32_e32 v38, v106, v140
	v_mul_f32_e32 v39, v107, v141
	v_add_u32_e32 v111, 0xc800, v20
	v_cvt_pk_bf16_f32 v110, v38, v39
	v_mul_f32_e32 v38, v48, v16
	v_mul_f32_e32 v39, v49, v17
	v_sub_f32_e32 v130, 1.0, v130
	v_sub_f32_e32 v131, 1.0, v131
	v_cvt_pk_bf16_f32 v38, v38, v39
	ds_write2_b32 v127, v37, v38 offset0:136 offset1:204
	v_mul_f32_e32 v38, v48, v122
	v_mul_f32_e32 v39, v49, v123
	v_mul_f32_e32 v48, v132, v108
	v_mul_f32_e32 v49, v133, v109
	v_cvt_pk_bf16_f32 v37, v38, v39
	v_mul_f32_e32 v38, v48, v140
	v_mul_f32_e32 v39, v49, v141
	ds_write2_b32 v111, v41, v37 offset0:8 offset1:76
	v_cvt_pk_bf16_f32 v37, v38, v39
	v_mul_f32_e32 v38, v46, v16
	v_mul_f32_e32 v39, v47, v17
	ds_write2_b32 v40, v110, v37 offset0:136 offset1:204
	v_cvt_pk_bf16_f32 v37, v38, v39
	v_mul_f32_e32 v38, v46, v122
	v_mul_f32_e32 v39, v47, v123
	v_mul_f32_e32 v46, v130, v112
	v_mul_f32_e32 v47, v131, v113
	v_cvt_pk_bf16_f32 v40, v38, v39
	v_mul_f32_e32 v38, v46, v140
	v_mul_f32_e32 v39, v47, v141
	v_add_u32_e32 v110, 0xa800, v20
	v_cvt_pk_bf16_f32 v41, v38, v39
	v_mul_f32_e32 v38, v44, v16
	v_mul_f32_e32 v39, v45, v17
	v_sub_f32_e32 v134, 1.0, v134
	v_sub_f32_e32 v135, 1.0, v135
	v_cvt_pk_bf16_f32 v38, v38, v39
	ds_write2_b32 v110, v37, v38 offset0:16 offset1:84
	v_mul_f32_e32 v38, v44, v122
	v_mul_f32_e32 v39, v45, v123
	v_mul_f32_e32 v44, v136, v114
	v_mul_f32_e32 v45, v137, v115
	v_cvt_pk_bf16_f32 v37, v38, v39
	v_mul_f32_e32 v38, v44, v140
	v_mul_f32_e32 v39, v45, v141
	ds_write2_b32 v111, v40, v37 offset0:144 offset1:212
	v_cvt_pk_bf16_f32 v37, v38, v39
	v_add_u32_e32 v40, 0xec00, v20
	v_mul_f32_e32 v38, v42, v16
	v_mul_f32_e32 v39, v43, v17
	v_mul_f32_e32 v16, v52, v16
	v_mul_f32_e32 v17, v53, v17
	ds_write2_b32 v40, v41, v37 offset0:16 offset1:84
	v_cvt_pk_bf16_f32 v37, v38, v39
	v_cvt_pk_bf16_f32 v16, v16, v17
	v_mul_f32_e32 v38, v42, v122
	v_mul_f32_e32 v39, v43, v123
	ds_write2_b32 v110, v37, v16 offset0:152 offset1:220
	v_mul_f32_e32 v16, v52, v122
	v_mul_f32_e32 v17, v53, v123
	v_cvt_pk_bf16_f32 v41, v38, v39
	v_mul_f32_e32 v108, v134, v116
	v_mul_f32_e32 v109, v135, v117
	v_cvt_pk_bf16_f32 v16, v16, v17
	v_add_u32_e32 v17, 0xcc00, v20
	v_mul_f32_e32 v38, v108, v140
	v_mul_f32_e32 v39, v109, v141
	ds_write2_b32 v17, v41, v16 offset0:24 offset1:92
	v_mul_f32_e32 v16, v138, v118
	v_mul_f32_e32 v17, v139, v119
	v_cvt_pk_bf16_f32 v42, v38, v39
	v_mul_f32_e32 v38, v16, v140
	v_mul_f32_e32 v39, v17, v141
	v_exp_f32_e32 v52, v146
	v_cvt_pk_bf16_f32 v37, v38, v39
	ds_write2_b32 v40, v42, v37 offset0:152 offset1:220
	v_mov_b32_e32 v38, v124
	v_mov_b32_e32 v39, v50
	v_mov_b32_e32 v40, v106
	v_mov_b32_e32 v41, v48
	v_mul_f32_e32 v38, v38, v142
	v_mul_f32_e32 v39, v39, v142
	v_mul_f32_e32 v40, v40, v142
	v_mul_f32_e32 v41, v41, v142
	v_cvt_pk_bf16_f32 v38, v38, v39
	v_cvt_pk_bf16_f32 v39, v40, v41
	v_mov_b32_e32 v40, v46
	v_mov_b32_e32 v41, v44
	v_mov_b32_e32 v42, v108
	v_mov_b32_e32 v43, v16
	v_mul_f32_e32 v40, v40, v142
	v_mul_f32_e32 v41, v41, v142
	v_mul_f32_e32 v42, v42, v142
	v_mul_f32_e32 v43, v43, v142
	v_mov_b32_e32 v50, v125
	v_mov_b32_e32 v48, v107
	v_mov_b32_e32 v44, v47
	v_mov_b32_e32 v16, v109
	v_cvt_pk_bf16_f32 v40, v40, v41
	v_cvt_pk_bf16_f32 v41, v42, v43
	v_mul_f32_e32 v42, v50, v52
	v_mul_f32_e32 v43, v51, v52
	v_mul_f32_e32 v48, v48, v52
	v_mul_f32_e32 v49, v49, v52
	v_mul_f32_e32 v44, v44, v52
	v_mul_f32_e32 v45, v45, v52
	v_mul_f32_e32 v16, v16, v52
	v_mul_f32_e32 v17, v17, v52
	v_cvt_pk_bf16_f32 v42, v42, v43
	v_cvt_pk_bf16_f32 v43, v48, v49
	v_cvt_pk_bf16_f32 v44, v44, v45
	v_cvt_pk_bf16_f32 v45, v16, v17
	s_and_b64 vcc, exec, s[72:73]
	ds_write_b128 v19, v[38:41]
	ds_write_b128 v19, v[42:45] offset:80
	s_cbranch_vccnz .LBB0_429
	v_exp_f32_e32 v14, v14
	v_exp_f32_e32 v15, v15
	ds_write_b64 v100, v[14:15]
	s_branch .LBB0_429
